# LN1 preamble router-weight transpose: 8 loads in flight per iteration instead of pairs with a full wait each
# baseline (speedup 1.0000x reference)
; __device__ __forceinline__ void phase_ln1(const Args& a, LAS unsigned char* lds, const WCtx& w, int l, int nrows) {
;     ...
;     for (int i = w.tid; i < 16384; i += NTHREADS) { const int d = i >> 4, e = i & 15; WRT[e * 1024 + d] = a.in[I_WROUTER][(size_t)l * 16384 + i]; }
.LBB0_2141:
	v_mov_b32_e32 v10, v2
	v_mov_b32_e32 v11, v51
	v_lshl_add_u64 v[10:11], v[10:11], 2, s[4:5]
	v_add_u32_e32 v12, 0x400, v2
	v_mov_b32_e32 v13, v51
	v_lshl_add_u64 v[12:13], v[12:13], 2, s[4:5]
	v_add_u32_e32 v14, 0x800, v2
	v_mov_b32_e32 v15, v51
	v_lshl_add_u64 v[14:15], v[14:15], 2, s[4:5]
	v_add_u32_e32 v24, 0xc00, v2
	v_mov_b32_e32 v25, v51
	v_lshl_add_u64 v[24:25], v[24:25], 2, s[4:5]
	global_load_dword v16, v[10:11], off
	global_load_dword v17, v[10:11], off offset:2048
	global_load_dword v18, v[12:13], off
	global_load_dword v19, v[12:13], off offset:2048
	global_load_dword v20, v[14:15], off
	global_load_dword v21, v[14:15], off offset:2048
	global_load_dword v22, v[24:25], off
	global_load_dword v23, v[24:25], off offset:2048
	v_lshlrev_b32_e32 v8, 10, v2
	v_and_b32_e32 v8, 0x3c00, v8
	v_ashrrev_i32_e32 v9, 4, v2
	v_lshl_add_u32 v8, v8, 2, 0
	v_lshl_add_u32 v9, v9, 2, v8
	v_add_u32_e32 v6, -4, v6
	v_cmp_eq_u32_e32 vcc, 0, v6
	s_or_b64 s[8:9], vcc, s[8:9]
	v_add_u32_e32 v3, 0x1000, v3
	v_add_u32_e32 v2, 0x1000, v2
	s_waitcnt vmcnt(0)
	ds_write_b32 v9, v16
	ds_write_b32 v9, v17 offset:128
	ds_write_b32 v9, v18 offset:256
	ds_write_b32 v9, v19 offset:384
	ds_write_b32 v9, v20 offset:512
	ds_write_b32 v9, v21 offset:640
	ds_write_b32 v9, v22 offset:768
	ds_write_b32 v9, v23 offset:896
	s_andn2_b64 exec, exec, s[8:9]
	s_cbranch_execnz .LBB0_2141
	s_or_b64 exec, exec, s[8:9]
